# attention leaders: next-tile LDS-DMA issue block rewritten with scalar address/M0 arithmetic (10 VALU-port instructions instead of 38) and a scalar branch instead of an exec mask; on top of v50
# speedup vs baseline: 1.0749x; 1.0069x over previous
.LBB0_233:
	s_waitcnt vmcnt(0)
	s_waitcnt lgkmcnt(0)
	s_barrier
	s_add_i32 s6, s90, 1
	s_cmp_lg_u32 s90, 2
	s_cselect_b32 s33, s6, 0
	v_cmp_ge_i32_e32 vcc, v141, v155
	v_add_u32_e32 v126, 64, v66
	s_mov_b64 s[86:87], 0
	s_cbranch_vccnz .LBB0_232
	v_readfirstlane_b32 s98, v126
	v_readfirstlane_b32 s99, v191
	s_lshl_b32 s6, s33, 15
	s_mov_b32 s101, 0
	s_mov_b32 s7, 0
	s_add_i32 s99, s99, s6
	s_lshl_b32 s100, s98, 11
	s_lshl_b32 s6, s98, 1
	v_lshl_add_u64 v[70:71], v[106:107], 0, s[100:101]
	s_mov_b32 m0, s99
	s_add_u32 s100, s100, 0x8000
	global_load_lds_dwordx4 v[70:71], off
	v_lshl_add_u64 v[68:69], v[108:109], 0, s[6:7]
	s_add_i32 m0, s99, 0x4000
	s_add_u32 s6, s6, 0x40000
	global_load_lds_dwordx4 v[68:69], off
	v_lshl_add_u64 v[70:71], v[106:107], 0, s[100:101]
	s_add_i32 m0, s99, 0x1000
	s_add_u32 s100, s100, 0x8000
	global_load_lds_dwordx4 v[70:71], off
	v_lshl_add_u64 v[68:69], v[108:109], 0, s[6:7]
	s_add_i32 m0, s99, 0x5000
	s_add_u32 s6, s6, 0x40000
	global_load_lds_dwordx4 v[68:69], off
	v_lshl_add_u64 v[70:71], v[106:107], 0, s[100:101]
	s_add_i32 m0, s99, 0x2000
	s_add_u32 s100, s100, 0x8000
	global_load_lds_dwordx4 v[70:71], off
	v_lshl_add_u64 v[68:69], v[108:109], 0, s[6:7]
	s_add_i32 m0, s99, 0x6000
	s_add_u32 s6, s6, 0x40000
	global_load_lds_dwordx4 v[68:69], off
	v_lshl_add_u64 v[70:71], v[106:107], 0, s[100:101]
	s_add_i32 m0, s99, 0x3000
	s_add_u32 s100, s100, 0x8000
	global_load_lds_dwordx4 v[70:71], off
	v_lshl_add_u64 v[68:69], v[108:109], 0, s[6:7]
	s_add_i32 m0, s99, 0x7000
	s_add_u32 s6, s6, 0x40000
	global_load_lds_dwordx4 v[68:69], off
	s_branch .LBB0_232

	.amdhsa_kernel _Z14fwd_megakernel6Params
		.amdhsa_group_segment_fixed_size 133120
		.amdhsa_private_segment_fixed_size 0
		.amdhsa_kernarg_size 648
		.amdhsa_user_sgpr_count 2
		.amdhsa_user_sgpr_dispatch_ptr 0
		.amdhsa_user_sgpr_queue_ptr 0
		.amdhsa_user_sgpr_kernarg_segment_ptr 1
		.amdhsa_user_sgpr_dispatch_id 0
		.amdhsa_user_sgpr_kernarg_preload_length 0
		.amdhsa_user_sgpr_kernarg_preload_offset 0
		.amdhsa_user_sgpr_private_segment_size 0
		.amdhsa_uses_dynamic_stack 0
		.amdhsa_enable_private_segment 0
		.amdhsa_system_sgpr_workgroup_id_x 1
		.amdhsa_system_sgpr_workgroup_id_y 0
		.amdhsa_system_sgpr_workgroup_id_z 0
		.amdhsa_system_sgpr_workgroup_info 0
		.amdhsa_system_vgpr_workitem_id 0
		.amdhsa_next_free_vgpr 256
		.amdhsa_next_free_sgpr 102
		.amdhsa_accum_offset 256
		.amdhsa_reserve_vcc 1
		.amdhsa_float_round_mode_32 0
		.amdhsa_float_round_mode_16_64 0
		.amdhsa_float_denorm_mode_32 3
		.amdhsa_float_denorm_mode_16_64 3
		.amdhsa_dx10_clamp 1
		.amdhsa_ieee_mode 1
		.amdhsa_fp16_overflow 0
		.amdhsa_tg_split 0
		.amdhsa_exception_fp_ieee_invalid_op 0
		.amdhsa_exception_fp_denorm_src 0
		.amdhsa_exception_fp_ieee_div_zero 0
		.amdhsa_exception_fp_ieee_overflow 0
		.amdhsa_exception_fp_ieee_underflow 0
		.amdhsa_exception_fp_ieee_inexact 0
		.amdhsa_exception_int_div_zero 0
	.end_amdhsa_kernel

.Lfunc_end0:
	.size	_Z14fwd_megakernel6Params, .Lfunc_end0-_Z14fwd_megakernel6Params
	.set _Z14fwd_megakernel6Params.num_vgpr, 256
	.set _Z14fwd_megakernel6Params.num_agpr, 0
	.set _Z14fwd_megakernel6Params.numbered_sgpr, 102
	.set _Z14fwd_megakernel6Params.num_named_barrier, 0
	.set _Z14fwd_megakernel6Params.private_seg_size, 0
	.set _Z14fwd_megakernel6Params.uses_vcc, 1
	.set _Z14fwd_megakernel6Params.uses_flat_scratch, 0
	.set _Z14fwd_megakernel6Params.has_dyn_sized_stack, 0
	.set _Z14fwd_megakernel6Params.has_recursion, 0
	.set _Z14fwd_megakernel6Params.has_indirect_call, 0

amdhsa.kernels:
  - .agpr_count:     0
    .args:
      - .offset:         0
        .size:           392
        .value_kind:     by_value
      - .offset:         392
        .size:           4
        .value_kind:     hidden_block_count_x
      - .offset:         396
        .size:           4
        .value_kind:     hidden_block_count_y
      - .offset:         400
        .size:           4
        .value_kind:     hidden_block_count_z
      - .offset:         404
        .size:           2
        .value_kind:     hidden_group_size_x
      - .offset:         406
        .size:           2
        .value_kind:     hidden_group_size_y
      - .offset:         408
        .size:           2
        .value_kind:     hidden_group_size_z
      - .offset:         410
        .size:           2
        .value_kind:     hidden_remainder_x
      - .offset:         412
        .size:           2
        .value_kind:     hidden_remainder_y
      - .offset:         414
        .size:           2
        .value_kind:     hidden_remainder_z
      - .offset:         432
        .size:           8
        .value_kind:     hidden_global_offset_x
      - .offset:         440
        .size:           8
        .value_kind:     hidden_global_offset_y
      - .offset:         448
        .size:           8
        .value_kind:     hidden_global_offset_z
      - .offset:         456
        .size:           2
        .value_kind:     hidden_grid_dims
    .group_segment_fixed_size: 133120
    .kernarg_segment_align: 8
    .kernarg_segment_size: 648
    .language:       OpenCL C
    .language_version:
      - 2
      - 0
    .max_flat_workgroup_size: 512
    .name:           _Z14fwd_megakernel6Params
    .private_segment_fixed_size: 0
    .sgpr_count:     108
    .sgpr_spill_count: 86
    .symbol:         _Z14fwd_megakernel6Params.kd
    .uniform_work_group_size: 1
    .uses_dynamic_stack: false
    .vgpr_count:     256
    .vgpr_spill_count: 0
    .wavefront_size: 64
